# v90 + knop3: same nop->ds_read fill in the S2/S3 K-loops (35 more s_nop removed)
# baseline (speedup 1.0000x reference)
.LBB0_824:
	ds_read_b128 v[156:159], v185
	ds_read_b128 v[160:163], v185 offset:1024
	ds_read_b128 v[164:167], v185 offset:2048
	ds_read_b128 v[168:171], v185 offset:3072
	ds_read_b128 v[172:175], v186
	ds_read_b128 v[188:191], v186 offset:1024
	ds_read_b128 v[192:195], v186 offset:2048
	ds_read_b128 v[196:199], v186 offset:3072
	s_add_i32 s41, s41, 2
	v_lshl_add_u64 v[176:177], s[38:39], 0, v[154:155]
	v_lshl_add_u64 v[176:177], v[176:177], 0, s[44:45]
	v_lshl_add_u64 v[182:183], v[176:177], 0, s[22:23]
	s_add_i32 m0, s5, 0xc000
	ds_read_b128 v[200:203], v187
	ds_read_b128 v[204:207], v187 offset:1024
	ds_read_b128 v[208:211], v187 offset:2048
	ds_read_b128 v[212:215], v187 offset:3072
	ds_read_b128 v[216:219], v187 offset:4096
	ds_read_b128 v[220:223], v187 offset:5120
	ds_read_b128 v[224:227], v187 offset:6144
	global_load_lds_dwordx4 v[182:183], off
	v_lshl_add_u64 v[182:183], s[38:39], 0, v[150:151]
	v_lshl_add_u64 v[182:183], v[182:183], 0, s[44:45]
	v_lshl_add_u64 v[232:233], v[182:183], 0, s[22:23]
	s_add_i32 m0, s5, 0xe000
	ds_read_b128 v[228:231], v187 offset:7168
	global_load_lds_dwordx4 v[232:233], off
	s_waitcnt vmcnt(8)
	s_waitcnt lgkmcnt(0)
	s_barrier
	s_setprio 1
	v_mfma_f32_16x16x32_bf16 v[70:73], v[156:159], v[200:203], v[70:73]
	v_mfma_f32_16x16x32_bf16 v[66:69], v[164:167], v[200:203], v[66:69]
	v_mfma_f32_16x16x32_bf16 v[86:89], v[156:159], v[208:211], v[86:89]
	v_mfma_f32_16x16x32_bf16 v[94:97], v[164:167], v[208:211], v[94:97]
	v_mfma_f32_16x16x32_bf16 v[110:113], v[156:159], v[216:219], v[110:113]
	v_mfma_f32_16x16x32_bf16 v[114:117], v[164:167], v[216:219], v[114:117]
	v_mfma_f32_16x16x32_bf16 v[126:129], v[156:159], v[224:227], v[126:129]
	v_mfma_f32_16x16x32_bf16 v[102:105], v[164:167], v[224:227], v[102:105]
	v_mfma_f32_16x16x32_bf16 v[70:73], v[160:163], v[204:207], v[70:73]
	v_mfma_f32_16x16x32_bf16 v[66:69], v[168:171], v[204:207], v[66:69]
	v_mfma_f32_16x16x32_bf16 v[86:89], v[160:163], v[212:215], v[86:89]
	v_mfma_f32_16x16x32_bf16 v[94:97], v[168:171], v[212:215], v[94:97]
	v_mfma_f32_16x16x32_bf16 v[110:113], v[160:163], v[220:223], v[110:113]
	v_mfma_f32_16x16x32_bf16 v[114:117], v[168:171], v[220:223], v[114:117]
	v_mfma_f32_16x16x32_bf16 v[126:129], v[160:163], v[228:231], v[126:129]
	v_mfma_f32_16x16x32_bf16 v[102:105], v[168:171], v[228:231], v[102:105]
	v_mfma_f32_16x16x32_bf16 v[74:77], v[172:175], v[200:203], v[74:77]
	v_mfma_f32_16x16x32_bf16 v[82:85], v[192:195], v[200:203], v[82:85]
	v_mfma_f32_16x16x32_bf16 v[98:101], v[172:175], v[208:211], v[98:101]
	v_mfma_f32_16x16x32_bf16 v[106:109], v[192:195], v[208:211], v[106:109]
	v_mfma_f32_16x16x32_bf16 v[118:121], v[172:175], v[216:219], v[118:121]
	v_mfma_f32_16x16x32_bf16 v[122:125], v[192:195], v[216:219], v[122:125]
	v_mfma_f32_16x16x32_bf16 v[90:93], v[172:175], v[224:227], v[90:93]
	v_mfma_f32_16x16x32_bf16 v[78:81], v[192:195], v[224:227], v[78:81]
	v_mfma_f32_16x16x32_bf16 v[74:77], v[188:191], v[204:207], v[74:77]
	v_mfma_f32_16x16x32_bf16 v[82:85], v[196:199], v[204:207], v[82:85]
	v_mfma_f32_16x16x32_bf16 v[98:101], v[188:191], v[212:215], v[98:101]
	v_mfma_f32_16x16x32_bf16 v[106:109], v[196:199], v[212:215], v[106:109]
	v_mfma_f32_16x16x32_bf16 v[118:121], v[188:191], v[220:223], v[118:121]
	v_mfma_f32_16x16x32_bf16 v[122:125], v[196:199], v[220:223], v[122:125]
	v_mfma_f32_16x16x32_bf16 v[90:93], v[188:191], v[228:231], v[90:93]
	v_mfma_f32_16x16x32_bf16 v[78:81], v[196:199], v[228:231], v[78:81]
	s_setprio 0
	s_barrier
	v_lshl_add_u64 v[232:233], s[36:37], 0, v[144:145]
	v_lshl_add_u64 v[232:233], v[232:233], 0, s[44:45]
	s_add_i32 s60, s57, s4
	v_lshl_add_u64 v[234:235], v[232:233], 0, s[26:27]
	s_mov_b32 m0, s60
	ds_read_b128 v[200:203], v187 offset:16384
	ds_read_b128 v[204:207], v187 offset:17408
	ds_read_b128 v[208:211], v187 offset:18432
	ds_read_b128 v[212:215], v187 offset:19456
	global_load_lds_dwordx4 v[234:235], off
	v_lshl_add_u64 v[234:235], s[36:37], 0, v[140:141]
	v_lshl_add_u64 v[234:235], v[234:235], 0, s[44:45]
	v_lshl_add_u64 v[236:237], v[234:235], 0, s[26:27]
	s_add_i32 m0, s60, 0x2000
	s_add_i32 s60, s58, s4
	global_load_lds_dwordx4 v[236:237], off
	v_lshl_add_u64 v[236:237], s[36:37], 0, v[146:147]
	v_lshl_add_u64 v[236:237], v[236:237], 0, s[44:45]
	v_lshl_add_u64 v[238:239], v[236:237], 0, s[26:27]
	s_mov_b32 m0, s60
	ds_read_b128 v[216:219], v187 offset:20480
	global_load_lds_dwordx4 v[238:239], off
	v_lshl_add_u64 v[238:239], s[36:37], 0, v[142:143]
	v_lshl_add_u64 v[238:239], v[238:239], 0, s[44:45]
	v_lshl_add_u64 v[240:241], v[238:239], 0, s[26:27]
	s_add_i32 m0, s60, 0x2000
	ds_read_b128 v[220:223], v187 offset:21504
	global_load_lds_dwordx4 v[240:241], off
	v_lshl_add_u64 v[240:241], s[38:39], 0, v[152:153]
	v_lshl_add_u64 v[240:241], v[240:241], 0, s[44:45]
	v_lshl_add_u64 v[242:243], v[240:241], 0, s[26:27]
	s_mov_b32 m0, s5
	ds_read_b128 v[224:227], v187 offset:22528
	global_load_lds_dwordx4 v[242:243], off
	v_lshl_add_u64 v[242:243], s[38:39], 0, v[148:149]
	v_lshl_add_u64 v[242:243], v[242:243], 0, s[44:45]
	v_lshl_add_u64 v[244:245], v[242:243], 0, s[26:27]
	s_mov_b32 m0, s46
	ds_read_b128 v[228:231], v187 offset:23552
	global_load_lds_dwordx4 v[244:245], off
	s_waitcnt vmcnt(8)
	s_waitcnt lgkmcnt(0)
	s_barrier
	s_setprio 1
	v_mfma_f32_16x16x32_bf16 v[62:65], v[156:159], v[200:203], v[62:65]
	v_mfma_f32_16x16x32_bf16 v[58:61], v[164:167], v[200:203], v[58:61]
	v_mfma_f32_16x16x32_bf16 v[46:49], v[156:159], v[208:211], v[46:49]
	v_mfma_f32_16x16x32_bf16 v[42:45], v[164:167], v[208:211], v[42:45]
	v_mfma_f32_16x16x32_bf16 v[30:33], v[156:159], v[216:219], v[30:33]
	v_mfma_f32_16x16x32_bf16 v[26:29], v[164:167], v[216:219], v[26:29]
	v_mfma_f32_16x16x32_bf16 v[14:17], v[156:159], v[224:227], v[14:17]
	v_mfma_f32_16x16x32_bf16 v[10:13], v[164:167], v[224:227], v[10:13]
	v_mfma_f32_16x16x32_bf16 v[62:65], v[160:163], v[204:207], v[62:65]
	v_mfma_f32_16x16x32_bf16 v[58:61], v[168:171], v[204:207], v[58:61]
	v_mfma_f32_16x16x32_bf16 v[46:49], v[160:163], v[212:215], v[46:49]
	v_mfma_f32_16x16x32_bf16 v[42:45], v[168:171], v[212:215], v[42:45]
	v_mfma_f32_16x16x32_bf16 v[30:33], v[160:163], v[220:223], v[30:33]
	v_mfma_f32_16x16x32_bf16 v[26:29], v[168:171], v[220:223], v[26:29]
	v_mfma_f32_16x16x32_bf16 v[14:17], v[160:163], v[228:231], v[14:17]
	v_mfma_f32_16x16x32_bf16 v[10:13], v[168:171], v[228:231], v[10:13]
	v_mfma_f32_16x16x32_bf16 v[54:57], v[172:175], v[200:203], v[54:57]
	v_mfma_f32_16x16x32_bf16 v[50:53], v[192:195], v[200:203], v[50:53]
	v_mfma_f32_16x16x32_bf16 v[38:41], v[172:175], v[208:211], v[38:41]
	v_mfma_f32_16x16x32_bf16 v[34:37], v[192:195], v[208:211], v[34:37]
	v_mfma_f32_16x16x32_bf16 v[22:25], v[172:175], v[216:219], v[22:25]
	v_mfma_f32_16x16x32_bf16 v[18:21], v[192:195], v[216:219], v[18:21]
	v_mfma_f32_16x16x32_bf16 v[6:9], v[172:175], v[224:227], v[6:9]
	v_mfma_f32_16x16x32_bf16 v[2:5], v[192:195], v[224:227], v[2:5]
	v_mfma_f32_16x16x32_bf16 v[54:57], v[188:191], v[204:207], v[54:57]
	v_mfma_f32_16x16x32_bf16 v[50:53], v[196:199], v[204:207], v[50:53]
	v_mfma_f32_16x16x32_bf16 v[38:41], v[188:191], v[212:215], v[38:41]
	v_mfma_f32_16x16x32_bf16 v[34:37], v[196:199], v[212:215], v[34:37]
	v_mfma_f32_16x16x32_bf16 v[22:25], v[188:191], v[220:223], v[22:25]
	v_mfma_f32_16x16x32_bf16 v[18:21], v[196:199], v[220:223], v[18:21]
	v_mfma_f32_16x16x32_bf16 v[6:9], v[188:191], v[228:231], v[6:9]
	v_mfma_f32_16x16x32_bf16 v[2:5], v[196:199], v[228:231], v[2:5]
	s_setprio 0
	s_barrier
	s_add_i32 s60, 0, 0x18000
	v_add_u32_e32 v138, s60, v181
	s_add_i32 s61, 0, 0x1c000
	ds_read_b128 v[156:159], v138
	ds_read_b128 v[160:163], v138 offset:1024
	ds_read_b128 v[164:167], v138 offset:2048
	ds_read_b128 v[168:171], v138 offset:3072
	v_add_u32_e32 v138, s61, v181
	ds_read_b128 v[172:175], v138
	ds_read_b128 v[188:191], v138 offset:1024
	ds_read_b128 v[192:195], v138 offset:2048
	ds_read_b128 v[196:199], v138 offset:3072
	s_mov_b32 m0, s47
	v_lshl_add_u64 v[176:177], v[176:177], 0, s[26:27]
	ds_read_b128 v[200:203], v187 offset:32768
	ds_read_b128 v[204:207], v187 offset:33792
	ds_read_b128 v[208:211], v187 offset:34816
	ds_read_b128 v[212:215], v187 offset:35840
	ds_read_b128 v[216:219], v187 offset:36864
	ds_read_b128 v[220:223], v187 offset:37888
	ds_read_b128 v[224:227], v187 offset:38912
	global_load_lds_dwordx4 v[176:177], off
	v_lshl_add_u64 v[176:177], v[182:183], 0, s[26:27]
	s_mov_b32 m0, s48
	ds_read_b128 v[228:231], v187 offset:39936
	global_load_lds_dwordx4 v[176:177], off
	s_waitcnt vmcnt(8)
	s_waitcnt lgkmcnt(0)
	s_barrier
	s_setprio 1
	v_mfma_f32_16x16x32_bf16 v[70:73], v[156:159], v[200:203], v[70:73]
	v_mfma_f32_16x16x32_bf16 v[66:69], v[164:167], v[200:203], v[66:69]
	v_mfma_f32_16x16x32_bf16 v[86:89], v[156:159], v[208:211], v[86:89]
	v_mfma_f32_16x16x32_bf16 v[94:97], v[164:167], v[208:211], v[94:97]
	v_mfma_f32_16x16x32_bf16 v[110:113], v[156:159], v[216:219], v[110:113]
	v_mfma_f32_16x16x32_bf16 v[114:117], v[164:167], v[216:219], v[114:117]
	v_mfma_f32_16x16x32_bf16 v[126:129], v[156:159], v[224:227], v[126:129]
	v_mfma_f32_16x16x32_bf16 v[102:105], v[164:167], v[224:227], v[102:105]
	v_mfma_f32_16x16x32_bf16 v[70:73], v[160:163], v[204:207], v[70:73]
	v_mfma_f32_16x16x32_bf16 v[66:69], v[168:171], v[204:207], v[66:69]
	v_mfma_f32_16x16x32_bf16 v[86:89], v[160:163], v[212:215], v[86:89]
	v_mfma_f32_16x16x32_bf16 v[94:97], v[168:171], v[212:215], v[94:97]
	v_mfma_f32_16x16x32_bf16 v[110:113], v[160:163], v[220:223], v[110:113]
	v_mfma_f32_16x16x32_bf16 v[114:117], v[168:171], v[220:223], v[114:117]
	v_mfma_f32_16x16x32_bf16 v[126:129], v[160:163], v[228:231], v[126:129]
	v_mfma_f32_16x16x32_bf16 v[102:105], v[168:171], v[228:231], v[102:105]
	v_mfma_f32_16x16x32_bf16 v[74:77], v[172:175], v[200:203], v[74:77]
	v_mfma_f32_16x16x32_bf16 v[82:85], v[192:195], v[200:203], v[82:85]
	v_mfma_f32_16x16x32_bf16 v[98:101], v[172:175], v[208:211], v[98:101]
	v_mfma_f32_16x16x32_bf16 v[106:109], v[192:195], v[208:211], v[106:109]
	v_mfma_f32_16x16x32_bf16 v[118:121], v[172:175], v[216:219], v[118:121]
	v_mfma_f32_16x16x32_bf16 v[122:125], v[192:195], v[216:219], v[122:125]
	v_mfma_f32_16x16x32_bf16 v[90:93], v[172:175], v[224:227], v[90:93]
	v_mfma_f32_16x16x32_bf16 v[78:81], v[192:195], v[224:227], v[78:81]
	v_mfma_f32_16x16x32_bf16 v[74:77], v[188:191], v[204:207], v[74:77]
	v_mfma_f32_16x16x32_bf16 v[82:85], v[196:199], v[204:207], v[82:85]
	v_mfma_f32_16x16x32_bf16 v[98:101], v[188:191], v[212:215], v[98:101]
	v_mfma_f32_16x16x32_bf16 v[106:109], v[196:199], v[212:215], v[106:109]
	v_mfma_f32_16x16x32_bf16 v[118:121], v[188:191], v[220:223], v[118:121]
	v_mfma_f32_16x16x32_bf16 v[122:125], v[196:199], v[220:223], v[122:125]
	v_mfma_f32_16x16x32_bf16 v[90:93], v[188:191], v[228:231], v[90:93]
	v_mfma_f32_16x16x32_bf16 v[78:81], v[196:199], v[228:231], v[78:81]
	s_setprio 0
	s_barrier
	s_add_i32 s60, s60, s4
	v_lshl_add_u64 v[176:177], v[232:233], 0, s[28:29]
	s_mov_b32 m0, s60
	ds_read_b128 v[200:203], v187 offset:49152
	ds_read_b128 v[204:207], v187 offset:50176
	ds_read_b128 v[208:211], v187 offset:51200
	ds_read_b128 v[212:215], v187 offset:52224
	global_load_lds_dwordx4 v[176:177], off
	v_lshl_add_u64 v[176:177], v[234:235], 0, s[28:29]
	s_add_i32 m0, s60, 0x2000
	s_add_i32 s60, s61, s4
	global_load_lds_dwordx4 v[176:177], off
	v_lshl_add_u64 v[176:177], v[236:237], 0, s[28:29]
	s_mov_b32 m0, s60
	ds_read_b128 v[216:219], v187 offset:53248
	global_load_lds_dwordx4 v[176:177], off
	v_lshl_add_u64 v[176:177], v[238:239], 0, s[28:29]
	s_add_i32 m0, s60, 0x2000
	ds_read_b128 v[220:223], v187 offset:54272
	global_load_lds_dwordx4 v[176:177], off
	v_lshl_add_u64 v[176:177], v[240:241], 0, s[28:29]
	s_mov_b32 m0, s49
	ds_read_b128 v[224:227], v187 offset:55296
	global_load_lds_dwordx4 v[176:177], off
	v_lshl_add_u64 v[176:177], v[242:243], 0, s[28:29]
	s_mov_b32 m0, s50
	ds_read_b128 v[228:231], v187 offset:56320
	global_load_lds_dwordx4 v[176:177], off
	s_waitcnt vmcnt(8)
	s_waitcnt lgkmcnt(0)
	s_barrier
	s_setprio 1
	v_mfma_f32_16x16x32_bf16 v[62:65], v[156:159], v[200:203], v[62:65]
	v_mfma_f32_16x16x32_bf16 v[58:61], v[164:167], v[200:203], v[58:61]
	v_mfma_f32_16x16x32_bf16 v[46:49], v[156:159], v[208:211], v[46:49]
	v_mfma_f32_16x16x32_bf16 v[42:45], v[164:167], v[208:211], v[42:45]
	v_mfma_f32_16x16x32_bf16 v[30:33], v[156:159], v[216:219], v[30:33]
	v_mfma_f32_16x16x32_bf16 v[26:29], v[164:167], v[216:219], v[26:29]
	v_mfma_f32_16x16x32_bf16 v[14:17], v[156:159], v[224:227], v[14:17]
	v_mfma_f32_16x16x32_bf16 v[10:13], v[164:167], v[224:227], v[10:13]
	v_mfma_f32_16x16x32_bf16 v[62:65], v[160:163], v[204:207], v[62:65]
	v_mfma_f32_16x16x32_bf16 v[58:61], v[168:171], v[204:207], v[58:61]
	v_mfma_f32_16x16x32_bf16 v[46:49], v[160:163], v[212:215], v[46:49]
	v_mfma_f32_16x16x32_bf16 v[42:45], v[168:171], v[212:215], v[42:45]
	v_mfma_f32_16x16x32_bf16 v[30:33], v[160:163], v[220:223], v[30:33]
	v_mfma_f32_16x16x32_bf16 v[26:29], v[168:171], v[220:223], v[26:29]
	v_mfma_f32_16x16x32_bf16 v[14:17], v[160:163], v[228:231], v[14:17]
	v_mfma_f32_16x16x32_bf16 v[10:13], v[168:171], v[228:231], v[10:13]
	v_mfma_f32_16x16x32_bf16 v[54:57], v[172:175], v[200:203], v[54:57]
	v_mfma_f32_16x16x32_bf16 v[50:53], v[192:195], v[200:203], v[50:53]
	v_mfma_f32_16x16x32_bf16 v[38:41], v[172:175], v[208:211], v[38:41]
	v_mfma_f32_16x16x32_bf16 v[34:37], v[192:195], v[208:211], v[34:37]
	v_mfma_f32_16x16x32_bf16 v[22:25], v[172:175], v[216:219], v[22:25]
	v_mfma_f32_16x16x32_bf16 v[18:21], v[192:195], v[216:219], v[18:21]
	v_mfma_f32_16x16x32_bf16 v[6:9], v[172:175], v[224:227], v[6:9]
	v_mfma_f32_16x16x32_bf16 v[2:5], v[192:195], v[224:227], v[2:5]
	v_mfma_f32_16x16x32_bf16 v[54:57], v[188:191], v[204:207], v[54:57]
	v_mfma_f32_16x16x32_bf16 v[50:53], v[196:199], v[204:207], v[50:53]
	v_mfma_f32_16x16x32_bf16 v[38:41], v[188:191], v[212:215], v[38:41]
	v_mfma_f32_16x16x32_bf16 v[34:37], v[196:199], v[212:215], v[34:37]
	v_mfma_f32_16x16x32_bf16 v[22:25], v[188:191], v[220:223], v[22:25]
	v_mfma_f32_16x16x32_bf16 v[18:21], v[196:199], v[220:223], v[18:21]
	v_mfma_f32_16x16x32_bf16 v[6:9], v[188:191], v[228:231], v[6:9]
	v_mfma_f32_16x16x32_bf16 v[2:5], v[196:199], v[228:231], v[2:5]
	s_setprio 0
	s_barrier
	s_add_u32 s44, s44, 0x100
	s_addc_u32 s45, s45, 0
	s_cmp_ge_i32 s41, s40
	s_cbranch_scc0 .LBB0_824
	s_branch .LBB0_826

.LBB0_828:
	ds_read_b128 v[158:161], v185
	ds_read_b128 v[162:165], v185 offset:1024
	ds_read_b128 v[166:169], v185 offset:2048
	ds_read_b128 v[170:173], v185 offset:3072
	ds_read_b128 v[174:177], v186
	ds_read_b128 v[190:193], v186 offset:1024
	ds_read_b128 v[194:197], v186 offset:2048
	ds_read_b128 v[198:201], v186 offset:3072
	s_add_i32 s42, s40, 1
	s_ashr_i32 s43, s42, 31
	s_lshl_b64 s[44:45], s[42:43], 7
	s_add_i32 s42, s40, 2
	s_add_u32 s43, s38, s0
	s_addc_u32 s41, s39, s1
	s_add_u32 s60, s36, s0
	s_addc_u32 s61, s37, s1
	s_cmp_eq_u32 s52, s40
	s_cselect_b32 s41, s13, s41
	s_cselect_b32 s40, s12, s43
	s_cselect_b32 s61, s35, s61
	s_cselect_b32 s60, s34, s60
	s_add_u32 s43, s38, s44
	s_addc_u32 s45, s39, s45
	s_add_u32 s44, s43, s8
	s_addc_u32 s45, s45, s9
	v_lshl_add_u64 v[182:183], s[44:45], 0, v[136:137]
	s_add_i32 m0, s5, 0xc000
	ds_read_b128 v[202:205], v187
	ds_read_b128 v[206:209], v187 offset:1024
	ds_read_b128 v[210:213], v187 offset:2048
	ds_read_b128 v[214:217], v187 offset:3072
	ds_read_b128 v[218:221], v187 offset:4096
	ds_read_b128 v[222:225], v187 offset:5120
	ds_read_b128 v[226:229], v187 offset:6144
	global_load_lds_dwordx4 v[182:183], off
	v_lshl_add_u64 v[182:183], s[44:45], 0, v[132:133]
	s_add_i32 m0, s5, 0xe000
	ds_read_b128 v[230:233], v187 offset:7168
	global_load_lds_dwordx4 v[182:183], off
	s_waitcnt vmcnt(8)
	s_waitcnt lgkmcnt(0)
	s_barrier
	s_setprio 1
	v_mfma_f32_16x16x32_bf16 v[70:73], v[158:161], v[202:205], v[70:73]
	v_mfma_f32_16x16x32_bf16 v[66:69], v[166:169], v[202:205], v[66:69]
	v_mfma_f32_16x16x32_bf16 v[86:89], v[158:161], v[210:213], v[86:89]
	v_mfma_f32_16x16x32_bf16 v[94:97], v[166:169], v[210:213], v[94:97]
	v_mfma_f32_16x16x32_bf16 v[110:113], v[158:161], v[218:221], v[110:113]
	v_mfma_f32_16x16x32_bf16 v[114:117], v[166:169], v[218:221], v[114:117]
	v_mfma_f32_16x16x32_bf16 v[126:129], v[158:161], v[226:229], v[126:129]
	v_mfma_f32_16x16x32_bf16 v[102:105], v[166:169], v[226:229], v[102:105]
	v_mfma_f32_16x16x32_bf16 v[70:73], v[162:165], v[206:209], v[70:73]
	v_mfma_f32_16x16x32_bf16 v[66:69], v[170:173], v[206:209], v[66:69]
	v_mfma_f32_16x16x32_bf16 v[86:89], v[162:165], v[214:217], v[86:89]
	v_mfma_f32_16x16x32_bf16 v[94:97], v[170:173], v[214:217], v[94:97]
	v_mfma_f32_16x16x32_bf16 v[110:113], v[162:165], v[222:225], v[110:113]
	v_mfma_f32_16x16x32_bf16 v[114:117], v[170:173], v[222:225], v[114:117]
	v_mfma_f32_16x16x32_bf16 v[126:129], v[162:165], v[230:233], v[126:129]
	v_mfma_f32_16x16x32_bf16 v[102:105], v[170:173], v[230:233], v[102:105]
	v_mfma_f32_16x16x32_bf16 v[74:77], v[174:177], v[202:205], v[74:77]
	v_mfma_f32_16x16x32_bf16 v[82:85], v[194:197], v[202:205], v[82:85]
	v_mfma_f32_16x16x32_bf16 v[98:101], v[174:177], v[210:213], v[98:101]
	v_mfma_f32_16x16x32_bf16 v[106:109], v[194:197], v[210:213], v[106:109]
	v_mfma_f32_16x16x32_bf16 v[118:121], v[174:177], v[218:221], v[118:121]
	v_mfma_f32_16x16x32_bf16 v[122:125], v[194:197], v[218:221], v[122:125]
	v_mfma_f32_16x16x32_bf16 v[90:93], v[174:177], v[226:229], v[90:93]
	v_mfma_f32_16x16x32_bf16 v[78:81], v[194:197], v[226:229], v[78:81]
	v_mfma_f32_16x16x32_bf16 v[74:77], v[190:193], v[206:209], v[74:77]
	v_mfma_f32_16x16x32_bf16 v[82:85], v[198:201], v[206:209], v[82:85]
	v_mfma_f32_16x16x32_bf16 v[98:101], v[190:193], v[214:217], v[98:101]
	v_mfma_f32_16x16x32_bf16 v[106:109], v[198:201], v[214:217], v[106:109]
	v_mfma_f32_16x16x32_bf16 v[118:121], v[190:193], v[222:225], v[118:121]
	v_mfma_f32_16x16x32_bf16 v[122:125], v[198:201], v[222:225], v[122:125]
	v_mfma_f32_16x16x32_bf16 v[90:93], v[190:193], v[230:233], v[90:93]
	v_mfma_f32_16x16x32_bf16 v[78:81], v[198:201], v[230:233], v[78:81]
	s_setprio 0
	s_barrier
	s_add_i32 s43, s57, s4
	v_lshl_add_u64 v[182:183], s[60:61], 0, v[134:135]
	s_mov_b32 m0, s43
	ds_read_b128 v[202:205], v187 offset:16384
	ds_read_b128 v[206:209], v187 offset:17408
	ds_read_b128 v[210:213], v187 offset:18432
	ds_read_b128 v[214:217], v187 offset:19456
	ds_read_b128 v[218:221], v187 offset:20480
	ds_read_b128 v[222:225], v187 offset:21504
	ds_read_b128 v[226:229], v187 offset:22528
	global_load_lds_dwordx4 v[182:183], off
	s_add_i32 m0, s43, 0x2000
	s_add_u32 s44, s60, s8
	v_lshl_add_u64 v[234:235], s[60:61], 0, v[130:131]
	s_addc_u32 s45, s61, s9
	s_add_i32 s43, s58, s4
	global_load_lds_dwordx4 v[234:235], off
	v_lshl_add_u64 v[236:237], s[44:45], 0, v[134:135]
	s_mov_b32 m0, s43
	v_lshl_add_u64 v[238:239], s[44:45], 0, v[130:131]
	global_load_lds_dwordx4 v[236:237], off
	s_add_i32 m0, s43, 0x2000
	v_lshl_add_u64 v[240:241], s[40:41], 0, v[136:137]
	global_load_lds_dwordx4 v[238:239], off
	s_mov_b32 m0, s5
	v_lshl_add_u64 v[242:243], s[40:41], 0, v[132:133]
	global_load_lds_dwordx4 v[240:241], off
	s_mov_b32 m0, s46
	ds_read_b128 v[230:233], v187 offset:23552
	global_load_lds_dwordx4 v[242:243], off
	s_waitcnt vmcnt(8)
	s_waitcnt lgkmcnt(0)
	s_barrier
	s_setprio 1
	v_mfma_f32_16x16x32_bf16 v[62:65], v[158:161], v[202:205], v[62:65]
	v_mfma_f32_16x16x32_bf16 v[58:61], v[166:169], v[202:205], v[58:61]
	v_mfma_f32_16x16x32_bf16 v[46:49], v[158:161], v[210:213], v[46:49]
	v_mfma_f32_16x16x32_bf16 v[42:45], v[166:169], v[210:213], v[42:45]
	v_mfma_f32_16x16x32_bf16 v[30:33], v[158:161], v[218:221], v[30:33]
	v_mfma_f32_16x16x32_bf16 v[26:29], v[166:169], v[218:221], v[26:29]
	v_mfma_f32_16x16x32_bf16 v[14:17], v[158:161], v[226:229], v[14:17]
	v_mfma_f32_16x16x32_bf16 v[10:13], v[166:169], v[226:229], v[10:13]
	v_mfma_f32_16x16x32_bf16 v[62:65], v[162:165], v[206:209], v[62:65]
	v_mfma_f32_16x16x32_bf16 v[58:61], v[170:173], v[206:209], v[58:61]
	v_mfma_f32_16x16x32_bf16 v[46:49], v[162:165], v[214:217], v[46:49]
	v_mfma_f32_16x16x32_bf16 v[42:45], v[170:173], v[214:217], v[42:45]
	v_mfma_f32_16x16x32_bf16 v[30:33], v[162:165], v[222:225], v[30:33]
	v_mfma_f32_16x16x32_bf16 v[26:29], v[170:173], v[222:225], v[26:29]
	v_mfma_f32_16x16x32_bf16 v[14:17], v[162:165], v[230:233], v[14:17]
	v_mfma_f32_16x16x32_bf16 v[10:13], v[170:173], v[230:233], v[10:13]
	v_mfma_f32_16x16x32_bf16 v[54:57], v[174:177], v[202:205], v[54:57]
	v_mfma_f32_16x16x32_bf16 v[50:53], v[194:197], v[202:205], v[50:53]
	v_mfma_f32_16x16x32_bf16 v[38:41], v[174:177], v[210:213], v[38:41]
	v_mfma_f32_16x16x32_bf16 v[34:37], v[194:197], v[210:213], v[34:37]
	v_mfma_f32_16x16x32_bf16 v[22:25], v[174:177], v[218:221], v[22:25]
	v_mfma_f32_16x16x32_bf16 v[18:21], v[194:197], v[218:221], v[18:21]
	v_mfma_f32_16x16x32_bf16 v[6:9], v[174:177], v[226:229], v[6:9]
	v_mfma_f32_16x16x32_bf16 v[2:5], v[194:197], v[226:229], v[2:5]
	v_mfma_f32_16x16x32_bf16 v[54:57], v[190:193], v[206:209], v[54:57]
	v_mfma_f32_16x16x32_bf16 v[50:53], v[198:201], v[206:209], v[50:53]
	v_mfma_f32_16x16x32_bf16 v[38:41], v[190:193], v[214:217], v[38:41]
	v_mfma_f32_16x16x32_bf16 v[34:37], v[198:201], v[214:217], v[34:37]
	v_mfma_f32_16x16x32_bf16 v[22:25], v[190:193], v[222:225], v[22:25]
	v_mfma_f32_16x16x32_bf16 v[18:21], v[198:201], v[222:225], v[18:21]
	v_mfma_f32_16x16x32_bf16 v[6:9], v[190:193], v[230:233], v[6:9]
	v_mfma_f32_16x16x32_bf16 v[2:5], v[198:201], v[230:233], v[2:5]
	s_setprio 0
	s_barrier
	s_add_i32 s43, 0, 0x18000
	v_add_u32_e32 v138, s43, v181
	s_add_i32 s44, 0, 0x1c000
	ds_read_b128 v[158:161], v138
	ds_read_b128 v[162:165], v138 offset:1024
	ds_read_b128 v[166:169], v138 offset:2048
	ds_read_b128 v[170:173], v138 offset:3072
	v_add_u32_e32 v138, s44, v181
	ds_read_b128 v[174:177], v138
	ds_read_b128 v[190:193], v138 offset:1024
	ds_read_b128 v[194:197], v138 offset:2048
	ds_read_b128 v[198:201], v138 offset:3072
	s_add_u32 s40, s40, s8
	s_addc_u32 s41, s41, s9
	s_mov_b32 m0, s47
	v_lshl_add_u64 v[244:245], s[40:41], 0, v[136:137]
	ds_read_b128 v[202:205], v187 offset:32768
	ds_read_b128 v[206:209], v187 offset:33792
	ds_read_b128 v[210:213], v187 offset:34816
	ds_read_b128 v[214:217], v187 offset:35840
	ds_read_b128 v[218:221], v187 offset:36864
	ds_read_b128 v[222:225], v187 offset:37888
	ds_read_b128 v[226:229], v187 offset:38912
	global_load_lds_dwordx4 v[244:245], off
	v_lshl_add_u64 v[244:245], s[40:41], 0, v[132:133]
	s_mov_b32 m0, s48
	ds_read_b128 v[230:233], v187 offset:39936
	global_load_lds_dwordx4 v[244:245], off
	s_waitcnt vmcnt(8)
	s_waitcnt lgkmcnt(0)
	s_barrier
	s_setprio 1
	v_mfma_f32_16x16x32_bf16 v[70:73], v[158:161], v[202:205], v[70:73]
	v_mfma_f32_16x16x32_bf16 v[66:69], v[166:169], v[202:205], v[66:69]
	v_mfma_f32_16x16x32_bf16 v[86:89], v[158:161], v[210:213], v[86:89]
	v_mfma_f32_16x16x32_bf16 v[94:97], v[166:169], v[210:213], v[94:97]
	v_mfma_f32_16x16x32_bf16 v[110:113], v[158:161], v[218:221], v[110:113]
	v_mfma_f32_16x16x32_bf16 v[114:117], v[166:169], v[218:221], v[114:117]
	v_mfma_f32_16x16x32_bf16 v[126:129], v[158:161], v[226:229], v[126:129]
	v_mfma_f32_16x16x32_bf16 v[102:105], v[166:169], v[226:229], v[102:105]
	v_mfma_f32_16x16x32_bf16 v[70:73], v[162:165], v[206:209], v[70:73]
	v_mfma_f32_16x16x32_bf16 v[66:69], v[170:173], v[206:209], v[66:69]
	v_mfma_f32_16x16x32_bf16 v[86:89], v[162:165], v[214:217], v[86:89]
	v_mfma_f32_16x16x32_bf16 v[94:97], v[170:173], v[214:217], v[94:97]
	v_mfma_f32_16x16x32_bf16 v[110:113], v[162:165], v[222:225], v[110:113]
	v_mfma_f32_16x16x32_bf16 v[114:117], v[170:173], v[222:225], v[114:117]
	v_mfma_f32_16x16x32_bf16 v[126:129], v[162:165], v[230:233], v[126:129]
	v_mfma_f32_16x16x32_bf16 v[102:105], v[170:173], v[230:233], v[102:105]
	v_mfma_f32_16x16x32_bf16 v[74:77], v[174:177], v[202:205], v[74:77]
	v_mfma_f32_16x16x32_bf16 v[82:85], v[194:197], v[202:205], v[82:85]
	v_mfma_f32_16x16x32_bf16 v[98:101], v[174:177], v[210:213], v[98:101]
	v_mfma_f32_16x16x32_bf16 v[106:109], v[194:197], v[210:213], v[106:109]
	v_mfma_f32_16x16x32_bf16 v[118:121], v[174:177], v[218:221], v[118:121]
	v_mfma_f32_16x16x32_bf16 v[122:125], v[194:197], v[218:221], v[122:125]
	v_mfma_f32_16x16x32_bf16 v[90:93], v[174:177], v[226:229], v[90:93]
	v_mfma_f32_16x16x32_bf16 v[78:81], v[194:197], v[226:229], v[78:81]
	v_mfma_f32_16x16x32_bf16 v[74:77], v[190:193], v[206:209], v[74:77]
	v_mfma_f32_16x16x32_bf16 v[82:85], v[198:201], v[206:209], v[82:85]
	v_mfma_f32_16x16x32_bf16 v[98:101], v[190:193], v[214:217], v[98:101]
	v_mfma_f32_16x16x32_bf16 v[106:109], v[198:201], v[214:217], v[106:109]
	v_mfma_f32_16x16x32_bf16 v[118:121], v[190:193], v[222:225], v[118:121]
	v_mfma_f32_16x16x32_bf16 v[122:125], v[198:201], v[222:225], v[122:125]
	v_mfma_f32_16x16x32_bf16 v[90:93], v[190:193], v[230:233], v[90:93]
	v_mfma_f32_16x16x32_bf16 v[78:81], v[198:201], v[230:233], v[78:81]
	s_setprio 0
	s_barrier
	s_add_i32 s40, s43, s4
	v_lshl_add_u64 v[182:183], v[182:183], 0, s[22:23]
	s_mov_b32 m0, s40
	ds_read_b128 v[202:205], v187 offset:49152
	ds_read_b128 v[206:209], v187 offset:50176
	ds_read_b128 v[210:213], v187 offset:51200
	ds_read_b128 v[214:217], v187 offset:52224
	global_load_lds_dwordx4 v[182:183], off
	v_lshl_add_u64 v[182:183], v[234:235], 0, s[22:23]
	s_add_i32 m0, s40, 0x2000
	s_add_i32 s40, s44, s4
	global_load_lds_dwordx4 v[182:183], off
	v_lshl_add_u64 v[182:183], v[236:237], 0, s[22:23]
	s_mov_b32 m0, s40
	ds_read_b128 v[218:221], v187 offset:53248
	global_load_lds_dwordx4 v[182:183], off
	v_lshl_add_u64 v[182:183], v[238:239], 0, s[22:23]
	s_add_i32 m0, s40, 0x2000
	ds_read_b128 v[222:225], v187 offset:54272
	global_load_lds_dwordx4 v[182:183], off
	v_lshl_add_u64 v[182:183], v[240:241], 0, s[22:23]
	s_mov_b32 m0, s49
	ds_read_b128 v[226:229], v187 offset:55296
	global_load_lds_dwordx4 v[182:183], off
	v_lshl_add_u64 v[182:183], v[242:243], 0, s[22:23]
	s_mov_b32 m0, s50
	ds_read_b128 v[230:233], v187 offset:56320
	global_load_lds_dwordx4 v[182:183], off
	s_waitcnt vmcnt(8)
	s_waitcnt lgkmcnt(0)
	s_barrier
	s_setprio 1
	v_mfma_f32_16x16x32_bf16 v[62:65], v[158:161], v[202:205], v[62:65]
	v_mfma_f32_16x16x32_bf16 v[58:61], v[166:169], v[202:205], v[58:61]
	v_mfma_f32_16x16x32_bf16 v[46:49], v[158:161], v[210:213], v[46:49]
	v_mfma_f32_16x16x32_bf16 v[42:45], v[166:169], v[210:213], v[42:45]
	v_mfma_f32_16x16x32_bf16 v[30:33], v[158:161], v[218:221], v[30:33]
	v_mfma_f32_16x16x32_bf16 v[26:29], v[166:169], v[218:221], v[26:29]
	v_mfma_f32_16x16x32_bf16 v[14:17], v[158:161], v[226:229], v[14:17]
	v_mfma_f32_16x16x32_bf16 v[10:13], v[166:169], v[226:229], v[10:13]
	v_mfma_f32_16x16x32_bf16 v[62:65], v[162:165], v[206:209], v[62:65]
	v_mfma_f32_16x16x32_bf16 v[58:61], v[170:173], v[206:209], v[58:61]
	v_mfma_f32_16x16x32_bf16 v[46:49], v[162:165], v[214:217], v[46:49]
	v_mfma_f32_16x16x32_bf16 v[42:45], v[170:173], v[214:217], v[42:45]
	v_mfma_f32_16x16x32_bf16 v[30:33], v[162:165], v[222:225], v[30:33]
	v_mfma_f32_16x16x32_bf16 v[26:29], v[170:173], v[222:225], v[26:29]
	v_mfma_f32_16x16x32_bf16 v[14:17], v[162:165], v[230:233], v[14:17]
	v_mfma_f32_16x16x32_bf16 v[10:13], v[170:173], v[230:233], v[10:13]
	v_mfma_f32_16x16x32_bf16 v[54:57], v[174:177], v[202:205], v[54:57]
	v_mfma_f32_16x16x32_bf16 v[50:53], v[194:197], v[202:205], v[50:53]
	v_mfma_f32_16x16x32_bf16 v[38:41], v[174:177], v[210:213], v[38:41]
	v_mfma_f32_16x16x32_bf16 v[34:37], v[194:197], v[210:213], v[34:37]
	v_mfma_f32_16x16x32_bf16 v[22:25], v[174:177], v[218:221], v[22:25]
	v_mfma_f32_16x16x32_bf16 v[18:21], v[194:197], v[218:221], v[18:21]
	v_mfma_f32_16x16x32_bf16 v[6:9], v[174:177], v[226:229], v[6:9]
	v_mfma_f32_16x16x32_bf16 v[2:5], v[194:197], v[226:229], v[2:5]
	v_mfma_f32_16x16x32_bf16 v[54:57], v[190:193], v[206:209], v[54:57]
	v_mfma_f32_16x16x32_bf16 v[50:53], v[198:201], v[206:209], v[50:53]
	v_mfma_f32_16x16x32_bf16 v[38:41], v[190:193], v[214:217], v[38:41]
	v_mfma_f32_16x16x32_bf16 v[34:37], v[198:201], v[214:217], v[34:37]
	v_mfma_f32_16x16x32_bf16 v[22:25], v[190:193], v[222:225], v[22:25]
	v_mfma_f32_16x16x32_bf16 v[18:21], v[198:201], v[222:225], v[18:21]
	v_mfma_f32_16x16x32_bf16 v[6:9], v[190:193], v[230:233], v[6:9]
	v_mfma_f32_16x16x32_bf16 v[2:5], v[198:201], v[230:233], v[2:5]
	s_setprio 0
	s_barrier
	s_add_u32 s0, s0, 0x100
	s_addc_u32 s1, s1, 0
	s_cmp_ge_i32 s42, s51
	s_mov_b32 s40, s42
	s_cbranch_scc0 .LBB0_828

.LBB0_902:
	s_mov_b64 s[28:29], s[10:11]
	s_mov_b32 s10, s37
	s_mov_b32 s0, s37
	s_add_i32 s37, s47, s1
	s_mov_b64 s[30:31], s[8:9]
	s_and_b64 s[8:9], s[26:27], exec
	s_cselect_b32 s8, s37, s10
	s_cselect_b32 s10, s46, s46
	s_ashr_i32 s11, s10, 31
	s_lshl_b64 s[10:11], s[10:11], 19
	s_add_u32 s10, s2, s10
	s_addc_u32 s11, s3, s11
	s_and_b64 s[34:35], s[26:27], exec
	s_cselect_b32 s1, s11, s29
	s_cselect_b32 s50, s10, s28
	s_ashr_i32 s9, s8, 31
	s_lshl_b64 s[8:9], s[8:9], 19
	s_add_u32 s8, s4, s8
	s_addc_u32 s9, s5, s9
	s_and_b64 s[34:35], s[26:27], exec
	s_cselect_b32 s51, s9, s31
	s_cselect_b32 s52, s8, s30
	s_add_u32 s28, s28, 0x40080
	s_addc_u32 s29, s29, 0
	s_add_u32 s53, s30, 0x100
	s_addc_u32 s54, s31, 0
	s_mov_b32 s55, -2
	s_waitcnt lgkmcnt(0)
	v_add_u32_e32 v254, 0x18000, v207
	v_add_u32_e32 v255, 0x1c000, v207
	ds_read_b128 v[130:133], v209
	ds_read_b128 v[134:137], v209 offset:1024
	ds_read_b128 v[138:141], v209 offset:2048
	ds_read_b128 v[142:145], v209 offset:3072
	ds_read_b128 v[146:149], v210
	ds_read_b128 v[150:153], v210 offset:1024
	ds_read_b128 v[154:157], v210 offset:2048
	ds_read_b128 v[158:161], v210 offset:3072
	s_add_u32 s30, s28, 0xfffc0080
	s_addc_u32 s31, s29, -1
	s_cmp_eq_u32 s55, 12
	s_cselect_b32 s35, s1, s31
	s_cselect_b32 s34, s50, s30
	s_cselect_b32 s31, s51, s54
	s_cselect_b32 s30, s52, s53
	v_lshl_add_u64 v[216:217], s[28:29], 0, v[190:191]
	s_add_i32 m0, s39, 0xc000
	ds_read_b128 v[162:165], v211
	ds_read_b128 v[166:169], v211 offset:1024
	ds_read_b128 v[170:173], v211 offset:2048
	ds_read_b128 v[174:177], v211 offset:3072
	ds_read_b128 v[194:197], v211 offset:4096
	ds_read_b128 v[198:201], v211 offset:5120
	ds_read_b128 v[202:205], v211 offset:6144
	global_load_lds_dwordx4 v[216:217], off
	v_lshl_add_u64 v[216:217], s[28:29], 0, v[192:193]
	s_add_i32 m0, s39, 0xe000
	ds_read_b128 v[212:215], v211 offset:7168
	global_load_lds_dwordx4 v[216:217], off
	s_waitcnt vmcnt(8)
	s_waitcnt lgkmcnt(0)
	s_barrier
	s_setprio 1
	v_mfma_f32_16x16x32_bf16 v[126:129], v[130:133], v[162:165], 0
	v_mfma_f32_16x16x32_bf16 v[122:125], v[138:141], v[162:165], 0
	v_mfma_f32_16x16x32_bf16 v[110:113], v[130:133], v[170:173], 0
	v_mfma_f32_16x16x32_bf16 v[106:109], v[138:141], v[170:173], 0
	v_mfma_f32_16x16x32_bf16 v[94:97], v[130:133], v[194:197], 0
	v_mfma_f32_16x16x32_bf16 v[90:93], v[138:141], v[194:197], 0
	v_mfma_f32_16x16x32_bf16 v[78:81], v[130:133], v[202:205], 0
	v_mfma_f32_16x16x32_bf16 v[74:77], v[138:141], v[202:205], 0
	v_mfma_f32_16x16x32_bf16 v[126:129], v[134:137], v[166:169], v[126:129]
	v_mfma_f32_16x16x32_bf16 v[122:125], v[142:145], v[166:169], v[122:125]
	v_mfma_f32_16x16x32_bf16 v[110:113], v[134:137], v[174:177], v[110:113]
	v_mfma_f32_16x16x32_bf16 v[106:109], v[142:145], v[174:177], v[106:109]
	v_mfma_f32_16x16x32_bf16 v[94:97], v[134:137], v[198:201], v[94:97]
	v_mfma_f32_16x16x32_bf16 v[90:93], v[142:145], v[198:201], v[90:93]
	v_mfma_f32_16x16x32_bf16 v[78:81], v[134:137], v[212:215], v[78:81]
	v_mfma_f32_16x16x32_bf16 v[74:77], v[142:145], v[212:215], v[74:77]
	v_mfma_f32_16x16x32_bf16 v[118:121], v[146:149], v[162:165], 0
	v_mfma_f32_16x16x32_bf16 v[114:117], v[154:157], v[162:165], 0
	v_mfma_f32_16x16x32_bf16 v[102:105], v[146:149], v[170:173], 0
	v_mfma_f32_16x16x32_bf16 v[98:101], v[154:157], v[170:173], 0
	v_mfma_f32_16x16x32_bf16 v[86:89], v[146:149], v[194:197], 0
	v_mfma_f32_16x16x32_bf16 v[82:85], v[154:157], v[194:197], 0
	v_mfma_f32_16x16x32_bf16 v[70:73], v[146:149], v[202:205], 0
	v_mfma_f32_16x16x32_bf16 v[66:69], v[154:157], v[202:205], 0
	v_mfma_f32_16x16x32_bf16 v[118:121], v[150:153], v[166:169], v[118:121]
	v_mfma_f32_16x16x32_bf16 v[114:117], v[158:161], v[166:169], v[114:117]
	v_mfma_f32_16x16x32_bf16 v[102:105], v[150:153], v[174:177], v[102:105]
	v_mfma_f32_16x16x32_bf16 v[98:101], v[158:161], v[174:177], v[98:101]
	v_mfma_f32_16x16x32_bf16 v[86:89], v[150:153], v[198:201], v[86:89]
	v_mfma_f32_16x16x32_bf16 v[82:85], v[158:161], v[198:201], v[82:85]
	v_mfma_f32_16x16x32_bf16 v[70:73], v[150:153], v[212:215], v[70:73]
	v_mfma_f32_16x16x32_bf16 v[66:69], v[158:161], v[212:215], v[66:69]
	s_setprio 0
	s_barrier
	s_add_i32 s56, s48, s38
	v_lshl_add_u64 v[216:217], s[30:31], 0, v[184:185]
	s_mov_b32 m0, s56
	ds_read_b128 v[162:165], v211 offset:16384
	ds_read_b128 v[166:169], v211 offset:17408
	ds_read_b128 v[170:173], v211 offset:18432
	ds_read_b128 v[174:177], v211 offset:19456
	ds_read_b128 v[194:197], v211 offset:20480
	global_load_lds_dwordx4 v[216:217], off
	s_add_i32 m0, s56, 0x2000
	s_add_u32 s56, s30, 0x40000
	v_lshl_add_u64 v[218:219], s[30:31], 0, v[188:189]
	s_addc_u32 s57, s31, 0
	s_add_i32 s58, s49, s38
	global_load_lds_dwordx4 v[218:219], off
	v_lshl_add_u64 v[220:221], s[56:57], 0, v[184:185]
	s_mov_b32 m0, s58
	v_lshl_add_u64 v[222:223], s[34:35], 0, v[186:187]
	global_load_lds_dwordx4 v[220:221], off
	v_lshl_add_u64 v[220:221], s[56:57], 0, v[188:189]
	s_add_i32 m0, s58, 0x2000
	ds_read_b128 v[198:201], v211 offset:21504
	global_load_lds_dwordx4 v[220:221], off
	v_lshl_add_u64 v[220:221], s[34:35], 0, v[182:183]
	s_mov_b32 m0, s39
	ds_read_b128 v[202:205], v211 offset:22528
	global_load_lds_dwordx4 v[220:221], off
	s_mov_b32 m0, s40
	ds_read_b128 v[212:215], v211 offset:23552
	global_load_lds_dwordx4 v[222:223], off
	s_waitcnt vmcnt(8)
	s_waitcnt lgkmcnt(0)
	s_barrier
	s_setprio 1
	v_mfma_f32_16x16x32_bf16 v[62:65], v[130:133], v[162:165], 0
	v_mfma_f32_16x16x32_bf16 v[58:61], v[138:141], v[162:165], 0
	v_mfma_f32_16x16x32_bf16 v[46:49], v[130:133], v[170:173], 0
	v_mfma_f32_16x16x32_bf16 v[42:45], v[138:141], v[170:173], 0
	v_mfma_f32_16x16x32_bf16 v[30:33], v[130:133], v[194:197], 0
	v_mfma_f32_16x16x32_bf16 v[26:29], v[138:141], v[194:197], 0
	v_mfma_f32_16x16x32_bf16 v[14:17], v[130:133], v[202:205], 0
	v_mfma_f32_16x16x32_bf16 v[10:13], v[138:141], v[202:205], 0
	v_mfma_f32_16x16x32_bf16 v[62:65], v[134:137], v[166:169], v[62:65]
	v_mfma_f32_16x16x32_bf16 v[58:61], v[142:145], v[166:169], v[58:61]
	v_mfma_f32_16x16x32_bf16 v[46:49], v[134:137], v[174:177], v[46:49]
	v_mfma_f32_16x16x32_bf16 v[42:45], v[142:145], v[174:177], v[42:45]
	v_mfma_f32_16x16x32_bf16 v[30:33], v[134:137], v[198:201], v[30:33]
	v_mfma_f32_16x16x32_bf16 v[26:29], v[142:145], v[198:201], v[26:29]
	v_mfma_f32_16x16x32_bf16 v[14:17], v[134:137], v[212:215], v[14:17]
	v_mfma_f32_16x16x32_bf16 v[10:13], v[142:145], v[212:215], v[10:13]
	v_mfma_f32_16x16x32_bf16 v[54:57], v[146:149], v[162:165], 0
	v_mfma_f32_16x16x32_bf16 v[50:53], v[154:157], v[162:165], 0
	v_mfma_f32_16x16x32_bf16 v[38:41], v[146:149], v[170:173], 0
	v_mfma_f32_16x16x32_bf16 v[34:37], v[154:157], v[170:173], 0
	v_mfma_f32_16x16x32_bf16 v[22:25], v[146:149], v[194:197], 0
	v_mfma_f32_16x16x32_bf16 v[18:21], v[154:157], v[194:197], 0
	v_mfma_f32_16x16x32_bf16 v[6:9], v[146:149], v[202:205], 0
	v_mfma_f32_16x16x32_bf16 v[2:5], v[154:157], v[202:205], 0
	v_mfma_f32_16x16x32_bf16 v[54:57], v[150:153], v[166:169], v[54:57]
	v_mfma_f32_16x16x32_bf16 v[50:53], v[158:161], v[166:169], v[50:53]
	v_mfma_f32_16x16x32_bf16 v[38:41], v[150:153], v[174:177], v[38:41]
	v_mfma_f32_16x16x32_bf16 v[34:37], v[158:161], v[174:177], v[34:37]
	v_mfma_f32_16x16x32_bf16 v[22:25], v[150:153], v[198:201], v[22:25]
	v_mfma_f32_16x16x32_bf16 v[18:21], v[158:161], v[198:201], v[18:21]
	v_mfma_f32_16x16x32_bf16 v[6:9], v[150:153], v[212:215], v[6:9]
	v_mfma_f32_16x16x32_bf16 v[2:5], v[158:161], v[212:215], v[2:5]
	s_setprio 0
	s_barrier
	s_add_i32 s56, 0, 0x18000
	s_add_i32 s57, 0, 0x1c000
	ds_read_b128 v[130:133], v254
	ds_read_b128 v[134:137], v254 offset:1024
	ds_read_b128 v[138:141], v254 offset:2048
	ds_read_b128 v[142:145], v254 offset:3072
	ds_read_b128 v[146:149], v255
	ds_read_b128 v[150:153], v255 offset:1024
	ds_read_b128 v[154:157], v255 offset:2048
	ds_read_b128 v[158:161], v255 offset:3072
	s_add_u32 s34, s34, 0x40000
	s_addc_u32 s35, s35, 0
	s_mov_b32 m0, s41
	v_lshl_add_u64 v[224:225], s[34:35], 0, v[182:183]
	ds_read_b128 v[162:165], v211 offset:32768
	ds_read_b128 v[166:169], v211 offset:33792
	ds_read_b128 v[170:173], v211 offset:34816
	ds_read_b128 v[174:177], v211 offset:35840
	ds_read_b128 v[194:197], v211 offset:36864
	ds_read_b128 v[198:201], v211 offset:37888
	ds_read_b128 v[202:205], v211 offset:38912
	global_load_lds_dwordx4 v[224:225], off
	v_lshl_add_u64 v[224:225], s[34:35], 0, v[186:187]
	s_mov_b32 m0, s42
	ds_read_b128 v[212:215], v211 offset:39936
	global_load_lds_dwordx4 v[224:225], off
	s_waitcnt vmcnt(8)
	s_waitcnt lgkmcnt(0)
	s_barrier
	s_setprio 1
	v_mfma_f32_16x16x32_bf16 v[126:129], v[130:133], v[162:165], v[126:129]
	v_mfma_f32_16x16x32_bf16 v[122:125], v[138:141], v[162:165], v[122:125]
	v_mfma_f32_16x16x32_bf16 v[110:113], v[130:133], v[170:173], v[110:113]
	v_mfma_f32_16x16x32_bf16 v[106:109], v[138:141], v[170:173], v[106:109]
	v_mfma_f32_16x16x32_bf16 v[94:97], v[130:133], v[194:197], v[94:97]
	v_mfma_f32_16x16x32_bf16 v[90:93], v[138:141], v[194:197], v[90:93]
	v_mfma_f32_16x16x32_bf16 v[78:81], v[130:133], v[202:205], v[78:81]
	v_mfma_f32_16x16x32_bf16 v[74:77], v[138:141], v[202:205], v[74:77]
	v_mfma_f32_16x16x32_bf16 v[126:129], v[134:137], v[166:169], v[126:129]
	v_mfma_f32_16x16x32_bf16 v[122:125], v[142:145], v[166:169], v[122:125]
	v_mfma_f32_16x16x32_bf16 v[110:113], v[134:137], v[174:177], v[110:113]
	v_mfma_f32_16x16x32_bf16 v[106:109], v[142:145], v[174:177], v[106:109]
	v_mfma_f32_16x16x32_bf16 v[94:97], v[134:137], v[198:201], v[94:97]
	v_mfma_f32_16x16x32_bf16 v[90:93], v[142:145], v[198:201], v[90:93]
	v_mfma_f32_16x16x32_bf16 v[78:81], v[134:137], v[212:215], v[78:81]
	v_mfma_f32_16x16x32_bf16 v[74:77], v[142:145], v[212:215], v[74:77]
	v_mfma_f32_16x16x32_bf16 v[118:121], v[146:149], v[162:165], v[118:121]
	v_mfma_f32_16x16x32_bf16 v[114:117], v[154:157], v[162:165], v[114:117]
	v_mfma_f32_16x16x32_bf16 v[102:105], v[146:149], v[170:173], v[102:105]
	v_mfma_f32_16x16x32_bf16 v[98:101], v[154:157], v[170:173], v[98:101]
	v_mfma_f32_16x16x32_bf16 v[86:89], v[146:149], v[194:197], v[86:89]
	v_mfma_f32_16x16x32_bf16 v[82:85], v[154:157], v[194:197], v[82:85]
	v_mfma_f32_16x16x32_bf16 v[70:73], v[146:149], v[202:205], v[70:73]
	v_mfma_f32_16x16x32_bf16 v[66:69], v[154:157], v[202:205], v[66:69]
	v_mfma_f32_16x16x32_bf16 v[118:121], v[150:153], v[166:169], v[118:121]
	v_mfma_f32_16x16x32_bf16 v[114:117], v[158:161], v[166:169], v[114:117]
	v_mfma_f32_16x16x32_bf16 v[102:105], v[150:153], v[174:177], v[102:105]
	v_mfma_f32_16x16x32_bf16 v[98:101], v[158:161], v[174:177], v[98:101]
	v_mfma_f32_16x16x32_bf16 v[86:89], v[150:153], v[198:201], v[86:89]
	v_mfma_f32_16x16x32_bf16 v[82:85], v[158:161], v[198:201], v[82:85]
	v_mfma_f32_16x16x32_bf16 v[70:73], v[150:153], v[212:215], v[70:73]
	v_mfma_f32_16x16x32_bf16 v[66:69], v[158:161], v[212:215], v[66:69]
	s_setprio 0
	s_barrier
	s_add_i32 s34, s56, s38
	v_lshl_add_u64 v[216:217], v[216:217], 0, s[22:23]
	s_mov_b32 m0, s34
	ds_read_b128 v[162:165], v211 offset:49152
	ds_read_b128 v[166:169], v211 offset:50176
	ds_read_b128 v[170:173], v211 offset:51200
	ds_read_b128 v[174:177], v211 offset:52224
	global_load_lds_dwordx4 v[216:217], off
	s_add_i32 m0, s34, 0x2000
	s_add_u32 s30, s30, 0x40080
	v_lshl_add_u64 v[216:217], v[218:219], 0, s[22:23]
	s_addc_u32 s31, s31, 0
	s_add_i32 s34, s57, s38
	global_load_lds_dwordx4 v[216:217], off
	v_lshl_add_u64 v[216:217], s[30:31], 0, v[184:185]
	s_mov_b32 m0, s34
	ds_read_b128 v[194:197], v211 offset:53248
	global_load_lds_dwordx4 v[216:217], off
	v_lshl_add_u64 v[216:217], s[30:31], 0, v[188:189]
	s_add_i32 m0, s34, 0x2000
	ds_read_b128 v[198:201], v211 offset:54272
	global_load_lds_dwordx4 v[216:217], off
	v_lshl_add_u64 v[216:217], v[220:221], 0, s[22:23]
	s_mov_b32 m0, s44
	ds_read_b128 v[202:205], v211 offset:55296
	global_load_lds_dwordx4 v[216:217], off
	v_lshl_add_u64 v[216:217], v[222:223], 0, s[22:23]
	s_mov_b32 m0, s45
	ds_read_b128 v[212:215], v211 offset:56320
	global_load_lds_dwordx4 v[216:217], off
	s_waitcnt vmcnt(8)
	s_waitcnt lgkmcnt(0)
	s_barrier
	s_setprio 1
	v_mfma_f32_16x16x32_bf16 v[62:65], v[130:133], v[162:165], v[62:65]
	v_mfma_f32_16x16x32_bf16 v[58:61], v[138:141], v[162:165], v[58:61]
	v_mfma_f32_16x16x32_bf16 v[46:49], v[130:133], v[170:173], v[46:49]
	v_mfma_f32_16x16x32_bf16 v[42:45], v[138:141], v[170:173], v[42:45]
	v_mfma_f32_16x16x32_bf16 v[30:33], v[130:133], v[194:197], v[30:33]
	v_mfma_f32_16x16x32_bf16 v[26:29], v[138:141], v[194:197], v[26:29]
	v_mfma_f32_16x16x32_bf16 v[14:17], v[130:133], v[202:205], v[14:17]
	v_mfma_f32_16x16x32_bf16 v[10:13], v[138:141], v[202:205], v[10:13]
	v_mfma_f32_16x16x32_bf16 v[62:65], v[134:137], v[166:169], v[62:65]
	v_mfma_f32_16x16x32_bf16 v[58:61], v[142:145], v[166:169], v[58:61]
	v_mfma_f32_16x16x32_bf16 v[46:49], v[134:137], v[174:177], v[46:49]
	v_mfma_f32_16x16x32_bf16 v[42:45], v[142:145], v[174:177], v[42:45]
	v_mfma_f32_16x16x32_bf16 v[30:33], v[134:137], v[198:201], v[30:33]
	v_mfma_f32_16x16x32_bf16 v[26:29], v[142:145], v[198:201], v[26:29]
	v_mfma_f32_16x16x32_bf16 v[14:17], v[134:137], v[212:215], v[14:17]
	v_mfma_f32_16x16x32_bf16 v[10:13], v[142:145], v[212:215], v[10:13]
	v_mfma_f32_16x16x32_bf16 v[54:57], v[146:149], v[162:165], v[54:57]
	v_mfma_f32_16x16x32_bf16 v[50:53], v[154:157], v[162:165], v[50:53]
	v_mfma_f32_16x16x32_bf16 v[38:41], v[146:149], v[170:173], v[38:41]
	v_mfma_f32_16x16x32_bf16 v[34:37], v[154:157], v[170:173], v[34:37]
	v_mfma_f32_16x16x32_bf16 v[22:25], v[146:149], v[194:197], v[22:25]
	v_mfma_f32_16x16x32_bf16 v[18:21], v[154:157], v[194:197], v[18:21]
	v_mfma_f32_16x16x32_bf16 v[6:9], v[146:149], v[202:205], v[6:9]
	v_mfma_f32_16x16x32_bf16 v[2:5], v[154:157], v[202:205], v[2:5]
	v_mfma_f32_16x16x32_bf16 v[54:57], v[150:153], v[166:169], v[54:57]
	v_mfma_f32_16x16x32_bf16 v[50:53], v[158:161], v[166:169], v[50:53]
	v_mfma_f32_16x16x32_bf16 v[38:41], v[150:153], v[174:177], v[38:41]
	v_mfma_f32_16x16x32_bf16 v[34:37], v[158:161], v[174:177], v[34:37]
	v_mfma_f32_16x16x32_bf16 v[22:25], v[150:153], v[198:201], v[22:25]
	v_mfma_f32_16x16x32_bf16 v[18:21], v[158:161], v[198:201], v[18:21]
	v_mfma_f32_16x16x32_bf16 v[6:9], v[150:153], v[212:215], v[6:9]
	v_mfma_f32_16x16x32_bf16 v[2:5], v[158:161], v[212:215], v[2:5]
	s_setprio 0
	s_barrier
	s_add_i32 s55, s55, 2
	s_add_u32 s28, s28, 0x100
	s_addc_u32 s29, s29, 0
	s_add_u32 s53, s53, 0x100
	s_addc_u32 s54, s54, 0
	s_cmp_gt_u32 s55, 13
	s_cbranch_scc1 .Lpeel_x3
.LBB0_903:
	ds_read_b128 v[130:133], v209
	ds_read_b128 v[134:137], v209 offset:1024
	ds_read_b128 v[138:141], v209 offset:2048
	ds_read_b128 v[142:145], v209 offset:3072
	ds_read_b128 v[146:149], v210
	ds_read_b128 v[150:153], v210 offset:1024
	ds_read_b128 v[154:157], v210 offset:2048
	ds_read_b128 v[158:161], v210 offset:3072
	s_add_u32 s30, s28, 0xfffc0080
	s_addc_u32 s31, s29, -1
	s_cmp_eq_u32 s55, 12
	s_cselect_b32 s35, s1, s31
	s_cselect_b32 s34, s50, s30
	s_cselect_b32 s31, s51, s54
	s_cselect_b32 s30, s52, s53
	v_lshl_add_u64 v[216:217], s[28:29], 0, v[190:191]
	s_add_i32 m0, s39, 0xc000
	ds_read_b128 v[162:165], v211
	ds_read_b128 v[166:169], v211 offset:1024
	ds_read_b128 v[170:173], v211 offset:2048
	ds_read_b128 v[174:177], v211 offset:3072
	ds_read_b128 v[194:197], v211 offset:4096
	ds_read_b128 v[198:201], v211 offset:5120
	ds_read_b128 v[202:205], v211 offset:6144
	global_load_lds_dwordx4 v[216:217], off
	v_lshl_add_u64 v[216:217], s[28:29], 0, v[192:193]
	s_add_i32 m0, s39, 0xe000
	ds_read_b128 v[212:215], v211 offset:7168
	global_load_lds_dwordx4 v[216:217], off
	s_waitcnt vmcnt(8)
	s_waitcnt lgkmcnt(0)
	s_barrier
	s_setprio 1
	v_mfma_f32_16x16x32_bf16 v[126:129], v[130:133], v[162:165], v[126:129]
	v_mfma_f32_16x16x32_bf16 v[122:125], v[138:141], v[162:165], v[122:125]
	v_mfma_f32_16x16x32_bf16 v[110:113], v[130:133], v[170:173], v[110:113]
	v_mfma_f32_16x16x32_bf16 v[106:109], v[138:141], v[170:173], v[106:109]
	v_mfma_f32_16x16x32_bf16 v[94:97], v[130:133], v[194:197], v[94:97]
	v_mfma_f32_16x16x32_bf16 v[90:93], v[138:141], v[194:197], v[90:93]
	v_mfma_f32_16x16x32_bf16 v[78:81], v[130:133], v[202:205], v[78:81]
	v_mfma_f32_16x16x32_bf16 v[74:77], v[138:141], v[202:205], v[74:77]
	v_mfma_f32_16x16x32_bf16 v[126:129], v[134:137], v[166:169], v[126:129]
	v_mfma_f32_16x16x32_bf16 v[122:125], v[142:145], v[166:169], v[122:125]
	v_mfma_f32_16x16x32_bf16 v[110:113], v[134:137], v[174:177], v[110:113]
	v_mfma_f32_16x16x32_bf16 v[106:109], v[142:145], v[174:177], v[106:109]
	v_mfma_f32_16x16x32_bf16 v[94:97], v[134:137], v[198:201], v[94:97]
	v_mfma_f32_16x16x32_bf16 v[90:93], v[142:145], v[198:201], v[90:93]
	v_mfma_f32_16x16x32_bf16 v[78:81], v[134:137], v[212:215], v[78:81]
	v_mfma_f32_16x16x32_bf16 v[74:77], v[142:145], v[212:215], v[74:77]
	v_mfma_f32_16x16x32_bf16 v[118:121], v[146:149], v[162:165], v[118:121]
	v_mfma_f32_16x16x32_bf16 v[114:117], v[154:157], v[162:165], v[114:117]
	v_mfma_f32_16x16x32_bf16 v[102:105], v[146:149], v[170:173], v[102:105]
	v_mfma_f32_16x16x32_bf16 v[98:101], v[154:157], v[170:173], v[98:101]
	v_mfma_f32_16x16x32_bf16 v[86:89], v[146:149], v[194:197], v[86:89]
	v_mfma_f32_16x16x32_bf16 v[82:85], v[154:157], v[194:197], v[82:85]
	v_mfma_f32_16x16x32_bf16 v[70:73], v[146:149], v[202:205], v[70:73]
	v_mfma_f32_16x16x32_bf16 v[66:69], v[154:157], v[202:205], v[66:69]
	v_mfma_f32_16x16x32_bf16 v[118:121], v[150:153], v[166:169], v[118:121]
	v_mfma_f32_16x16x32_bf16 v[114:117], v[158:161], v[166:169], v[114:117]
	v_mfma_f32_16x16x32_bf16 v[102:105], v[150:153], v[174:177], v[102:105]
	v_mfma_f32_16x16x32_bf16 v[98:101], v[158:161], v[174:177], v[98:101]
	v_mfma_f32_16x16x32_bf16 v[86:89], v[150:153], v[198:201], v[86:89]
	v_mfma_f32_16x16x32_bf16 v[82:85], v[158:161], v[198:201], v[82:85]
	v_mfma_f32_16x16x32_bf16 v[70:73], v[150:153], v[212:215], v[70:73]
	v_mfma_f32_16x16x32_bf16 v[66:69], v[158:161], v[212:215], v[66:69]
	s_setprio 0
	s_barrier
	s_add_i32 s56, s48, s38
	v_lshl_add_u64 v[216:217], s[30:31], 0, v[184:185]
	s_mov_b32 m0, s56
	ds_read_b128 v[162:165], v211 offset:16384
	ds_read_b128 v[166:169], v211 offset:17408
	ds_read_b128 v[170:173], v211 offset:18432
	ds_read_b128 v[174:177], v211 offset:19456
	ds_read_b128 v[194:197], v211 offset:20480
	global_load_lds_dwordx4 v[216:217], off
	s_add_i32 m0, s56, 0x2000
	s_add_u32 s56, s30, 0x40000
	v_lshl_add_u64 v[218:219], s[30:31], 0, v[188:189]
	s_addc_u32 s57, s31, 0
	s_add_i32 s58, s49, s38
	global_load_lds_dwordx4 v[218:219], off
	v_lshl_add_u64 v[220:221], s[56:57], 0, v[184:185]
	s_mov_b32 m0, s58
	v_lshl_add_u64 v[222:223], s[34:35], 0, v[186:187]
	global_load_lds_dwordx4 v[220:221], off
	v_lshl_add_u64 v[220:221], s[56:57], 0, v[188:189]
	s_add_i32 m0, s58, 0x2000
	ds_read_b128 v[198:201], v211 offset:21504
	global_load_lds_dwordx4 v[220:221], off
	v_lshl_add_u64 v[220:221], s[34:35], 0, v[182:183]
	s_mov_b32 m0, s39
	ds_read_b128 v[202:205], v211 offset:22528
	global_load_lds_dwordx4 v[220:221], off
	s_mov_b32 m0, s40
	ds_read_b128 v[212:215], v211 offset:23552
	global_load_lds_dwordx4 v[222:223], off
	s_waitcnt vmcnt(8)
	s_waitcnt lgkmcnt(0)
	s_barrier
	s_setprio 1
	v_mfma_f32_16x16x32_bf16 v[62:65], v[130:133], v[162:165], v[62:65]
	v_mfma_f32_16x16x32_bf16 v[58:61], v[138:141], v[162:165], v[58:61]
	v_mfma_f32_16x16x32_bf16 v[46:49], v[130:133], v[170:173], v[46:49]
	v_mfma_f32_16x16x32_bf16 v[42:45], v[138:141], v[170:173], v[42:45]
	v_mfma_f32_16x16x32_bf16 v[30:33], v[130:133], v[194:197], v[30:33]
	v_mfma_f32_16x16x32_bf16 v[26:29], v[138:141], v[194:197], v[26:29]
	v_mfma_f32_16x16x32_bf16 v[14:17], v[130:133], v[202:205], v[14:17]
	v_mfma_f32_16x16x32_bf16 v[10:13], v[138:141], v[202:205], v[10:13]
	v_mfma_f32_16x16x32_bf16 v[62:65], v[134:137], v[166:169], v[62:65]
	v_mfma_f32_16x16x32_bf16 v[58:61], v[142:145], v[166:169], v[58:61]
	v_mfma_f32_16x16x32_bf16 v[46:49], v[134:137], v[174:177], v[46:49]
	v_mfma_f32_16x16x32_bf16 v[42:45], v[142:145], v[174:177], v[42:45]
	v_mfma_f32_16x16x32_bf16 v[30:33], v[134:137], v[198:201], v[30:33]
	v_mfma_f32_16x16x32_bf16 v[26:29], v[142:145], v[198:201], v[26:29]
	v_mfma_f32_16x16x32_bf16 v[14:17], v[134:137], v[212:215], v[14:17]
	v_mfma_f32_16x16x32_bf16 v[10:13], v[142:145], v[212:215], v[10:13]
	v_mfma_f32_16x16x32_bf16 v[54:57], v[146:149], v[162:165], v[54:57]
	v_mfma_f32_16x16x32_bf16 v[50:53], v[154:157], v[162:165], v[50:53]
	v_mfma_f32_16x16x32_bf16 v[38:41], v[146:149], v[170:173], v[38:41]
	v_mfma_f32_16x16x32_bf16 v[34:37], v[154:157], v[170:173], v[34:37]
	v_mfma_f32_16x16x32_bf16 v[22:25], v[146:149], v[194:197], v[22:25]
	v_mfma_f32_16x16x32_bf16 v[18:21], v[154:157], v[194:197], v[18:21]
	v_mfma_f32_16x16x32_bf16 v[6:9], v[146:149], v[202:205], v[6:9]
	v_mfma_f32_16x16x32_bf16 v[2:5], v[154:157], v[202:205], v[2:5]
	v_mfma_f32_16x16x32_bf16 v[54:57], v[150:153], v[166:169], v[54:57]
	v_mfma_f32_16x16x32_bf16 v[50:53], v[158:161], v[166:169], v[50:53]
	v_mfma_f32_16x16x32_bf16 v[38:41], v[150:153], v[174:177], v[38:41]
	v_mfma_f32_16x16x32_bf16 v[34:37], v[158:161], v[174:177], v[34:37]
	v_mfma_f32_16x16x32_bf16 v[22:25], v[150:153], v[198:201], v[22:25]
	v_mfma_f32_16x16x32_bf16 v[18:21], v[158:161], v[198:201], v[18:21]
	v_mfma_f32_16x16x32_bf16 v[6:9], v[150:153], v[212:215], v[6:9]
	v_mfma_f32_16x16x32_bf16 v[2:5], v[158:161], v[212:215], v[2:5]
	s_setprio 0
	s_barrier
	s_add_i32 s56, 0, 0x18000
	s_add_i32 s57, 0, 0x1c000
	ds_read_b128 v[130:133], v254
	ds_read_b128 v[134:137], v254 offset:1024
	ds_read_b128 v[138:141], v254 offset:2048
	ds_read_b128 v[142:145], v254 offset:3072
	ds_read_b128 v[146:149], v255
	ds_read_b128 v[150:153], v255 offset:1024
	ds_read_b128 v[154:157], v255 offset:2048
	ds_read_b128 v[158:161], v255 offset:3072
	s_add_u32 s34, s34, 0x40000
	s_addc_u32 s35, s35, 0
	s_mov_b32 m0, s41
	v_lshl_add_u64 v[224:225], s[34:35], 0, v[182:183]
	ds_read_b128 v[162:165], v211 offset:32768
	ds_read_b128 v[166:169], v211 offset:33792
	ds_read_b128 v[170:173], v211 offset:34816
	ds_read_b128 v[174:177], v211 offset:35840
	ds_read_b128 v[194:197], v211 offset:36864
	ds_read_b128 v[198:201], v211 offset:37888
	ds_read_b128 v[202:205], v211 offset:38912
	global_load_lds_dwordx4 v[224:225], off
	v_lshl_add_u64 v[224:225], s[34:35], 0, v[186:187]
	s_mov_b32 m0, s42
	ds_read_b128 v[212:215], v211 offset:39936
	global_load_lds_dwordx4 v[224:225], off
	s_waitcnt vmcnt(8)
	s_waitcnt lgkmcnt(0)
	s_barrier
	s_setprio 1
	v_mfma_f32_16x16x32_bf16 v[126:129], v[130:133], v[162:165], v[126:129]
	v_mfma_f32_16x16x32_bf16 v[122:125], v[138:141], v[162:165], v[122:125]
	v_mfma_f32_16x16x32_bf16 v[110:113], v[130:133], v[170:173], v[110:113]
	v_mfma_f32_16x16x32_bf16 v[106:109], v[138:141], v[170:173], v[106:109]
	v_mfma_f32_16x16x32_bf16 v[94:97], v[130:133], v[194:197], v[94:97]
	v_mfma_f32_16x16x32_bf16 v[90:93], v[138:141], v[194:197], v[90:93]
	v_mfma_f32_16x16x32_bf16 v[78:81], v[130:133], v[202:205], v[78:81]
	v_mfma_f32_16x16x32_bf16 v[74:77], v[138:141], v[202:205], v[74:77]
	v_mfma_f32_16x16x32_bf16 v[126:129], v[134:137], v[166:169], v[126:129]
	v_mfma_f32_16x16x32_bf16 v[122:125], v[142:145], v[166:169], v[122:125]
	v_mfma_f32_16x16x32_bf16 v[110:113], v[134:137], v[174:177], v[110:113]
	v_mfma_f32_16x16x32_bf16 v[106:109], v[142:145], v[174:177], v[106:109]
	v_mfma_f32_16x16x32_bf16 v[94:97], v[134:137], v[198:201], v[94:97]
	v_mfma_f32_16x16x32_bf16 v[90:93], v[142:145], v[198:201], v[90:93]
	v_mfma_f32_16x16x32_bf16 v[78:81], v[134:137], v[212:215], v[78:81]
	v_mfma_f32_16x16x32_bf16 v[74:77], v[142:145], v[212:215], v[74:77]
	v_mfma_f32_16x16x32_bf16 v[118:121], v[146:149], v[162:165], v[118:121]
	v_mfma_f32_16x16x32_bf16 v[114:117], v[154:157], v[162:165], v[114:117]
	v_mfma_f32_16x16x32_bf16 v[102:105], v[146:149], v[170:173], v[102:105]
	v_mfma_f32_16x16x32_bf16 v[98:101], v[154:157], v[170:173], v[98:101]
	v_mfma_f32_16x16x32_bf16 v[86:89], v[146:149], v[194:197], v[86:89]
	v_mfma_f32_16x16x32_bf16 v[82:85], v[154:157], v[194:197], v[82:85]
	v_mfma_f32_16x16x32_bf16 v[70:73], v[146:149], v[202:205], v[70:73]
	v_mfma_f32_16x16x32_bf16 v[66:69], v[154:157], v[202:205], v[66:69]
	v_mfma_f32_16x16x32_bf16 v[118:121], v[150:153], v[166:169], v[118:121]
	v_mfma_f32_16x16x32_bf16 v[114:117], v[158:161], v[166:169], v[114:117]
	v_mfma_f32_16x16x32_bf16 v[102:105], v[150:153], v[174:177], v[102:105]
	v_mfma_f32_16x16x32_bf16 v[98:101], v[158:161], v[174:177], v[98:101]
	v_mfma_f32_16x16x32_bf16 v[86:89], v[150:153], v[198:201], v[86:89]
	v_mfma_f32_16x16x32_bf16 v[82:85], v[158:161], v[198:201], v[82:85]
	v_mfma_f32_16x16x32_bf16 v[70:73], v[150:153], v[212:215], v[70:73]
	v_mfma_f32_16x16x32_bf16 v[66:69], v[158:161], v[212:215], v[66:69]
	s_setprio 0
	s_barrier
	s_add_i32 s34, s56, s38
	v_lshl_add_u64 v[216:217], v[216:217], 0, s[22:23]
	s_mov_b32 m0, s34
	ds_read_b128 v[162:165], v211 offset:49152
	ds_read_b128 v[166:169], v211 offset:50176
	ds_read_b128 v[170:173], v211 offset:51200
	ds_read_b128 v[174:177], v211 offset:52224
	global_load_lds_dwordx4 v[216:217], off
	s_add_i32 m0, s34, 0x2000
	s_add_u32 s30, s30, 0x40080
	v_lshl_add_u64 v[216:217], v[218:219], 0, s[22:23]
	s_addc_u32 s31, s31, 0
	s_add_i32 s34, s57, s38
	global_load_lds_dwordx4 v[216:217], off
	v_lshl_add_u64 v[216:217], s[30:31], 0, v[184:185]
	s_mov_b32 m0, s34
	ds_read_b128 v[194:197], v211 offset:53248
	global_load_lds_dwordx4 v[216:217], off
	v_lshl_add_u64 v[216:217], s[30:31], 0, v[188:189]
	s_add_i32 m0, s34, 0x2000
	ds_read_b128 v[198:201], v211 offset:54272
	global_load_lds_dwordx4 v[216:217], off
	v_lshl_add_u64 v[216:217], v[220:221], 0, s[22:23]
	s_mov_b32 m0, s44
	ds_read_b128 v[202:205], v211 offset:55296
	global_load_lds_dwordx4 v[216:217], off
	v_lshl_add_u64 v[216:217], v[222:223], 0, s[22:23]
	s_mov_b32 m0, s45
	ds_read_b128 v[212:215], v211 offset:56320
	global_load_lds_dwordx4 v[216:217], off
	s_waitcnt vmcnt(8)
	s_waitcnt lgkmcnt(0)
	s_barrier
	s_setprio 1
	v_mfma_f32_16x16x32_bf16 v[62:65], v[130:133], v[162:165], v[62:65]
	v_mfma_f32_16x16x32_bf16 v[58:61], v[138:141], v[162:165], v[58:61]
	v_mfma_f32_16x16x32_bf16 v[46:49], v[130:133], v[170:173], v[46:49]
	v_mfma_f32_16x16x32_bf16 v[42:45], v[138:141], v[170:173], v[42:45]
	v_mfma_f32_16x16x32_bf16 v[30:33], v[130:133], v[194:197], v[30:33]
	v_mfma_f32_16x16x32_bf16 v[26:29], v[138:141], v[194:197], v[26:29]
	v_mfma_f32_16x16x32_bf16 v[14:17], v[130:133], v[202:205], v[14:17]
	v_mfma_f32_16x16x32_bf16 v[10:13], v[138:141], v[202:205], v[10:13]
	v_mfma_f32_16x16x32_bf16 v[62:65], v[134:137], v[166:169], v[62:65]
	v_mfma_f32_16x16x32_bf16 v[58:61], v[142:145], v[166:169], v[58:61]
	v_mfma_f32_16x16x32_bf16 v[46:49], v[134:137], v[174:177], v[46:49]
	v_mfma_f32_16x16x32_bf16 v[42:45], v[142:145], v[174:177], v[42:45]
	v_mfma_f32_16x16x32_bf16 v[30:33], v[134:137], v[198:201], v[30:33]
	v_mfma_f32_16x16x32_bf16 v[26:29], v[142:145], v[198:201], v[26:29]
	v_mfma_f32_16x16x32_bf16 v[14:17], v[134:137], v[212:215], v[14:17]
	v_mfma_f32_16x16x32_bf16 v[10:13], v[142:145], v[212:215], v[10:13]
	v_mfma_f32_16x16x32_bf16 v[54:57], v[146:149], v[162:165], v[54:57]
	v_mfma_f32_16x16x32_bf16 v[50:53], v[154:157], v[162:165], v[50:53]
	v_mfma_f32_16x16x32_bf16 v[38:41], v[146:149], v[170:173], v[38:41]
	v_mfma_f32_16x16x32_bf16 v[34:37], v[154:157], v[170:173], v[34:37]
	v_mfma_f32_16x16x32_bf16 v[22:25], v[146:149], v[194:197], v[22:25]
	v_mfma_f32_16x16x32_bf16 v[18:21], v[154:157], v[194:197], v[18:21]
	v_mfma_f32_16x16x32_bf16 v[6:9], v[146:149], v[202:205], v[6:9]
	v_mfma_f32_16x16x32_bf16 v[2:5], v[154:157], v[202:205], v[2:5]
	v_mfma_f32_16x16x32_bf16 v[54:57], v[150:153], v[166:169], v[54:57]
	v_mfma_f32_16x16x32_bf16 v[50:53], v[158:161], v[166:169], v[50:53]
	v_mfma_f32_16x16x32_bf16 v[38:41], v[150:153], v[174:177], v[38:41]
	v_mfma_f32_16x16x32_bf16 v[34:37], v[158:161], v[174:177], v[34:37]
	v_mfma_f32_16x16x32_bf16 v[22:25], v[150:153], v[198:201], v[22:25]
	v_mfma_f32_16x16x32_bf16 v[18:21], v[158:161], v[198:201], v[18:21]
	v_mfma_f32_16x16x32_bf16 v[6:9], v[150:153], v[212:215], v[6:9]
	v_mfma_f32_16x16x32_bf16 v[2:5], v[158:161], v[212:215], v[2:5]
	s_setprio 0
	s_barrier
	s_add_i32 s55, s55, 2
	s_add_u32 s28, s28, 0x100
	s_addc_u32 s29, s29, 0
	s_add_u32 s53, s53, 0x100
	s_addc_u32 s54, s54, 0
	s_cmp_gt_u32 s55, 13
	s_cbranch_scc0 .LBB0_903
